# L2 in-proj epilogue: ssq loads hoisted too, atomics no longer drained per row (plus previous L1-in hoist)
# speedup vs baseline: 1.0663x; 1.0019x over previous
; __device__ __forceinline__ float silu_f(float x) { return x * __builtin_amdgcn_rcpf(1.f + __expf(-x)); }
; __device__ __forceinline__ float gelu_f(float x) { const float u2 = 1.5957691216057308f * (x + 0.044715f * x * x * x); return x * __builtin_amdgcn_rcpf(1.f + __expf(-u2)); }
; __device__ __forceinline__ v4u pack8(const float (&y)[8]) { return (v4u){pk2(y[0], y[1]), pk2(y[2], y[3]), pk2(y[4], y[5]), pk2(y[6], y[7])}; }
;     __device__ __forceinline__ void operator()(const f32x4 (&acc)[2][2][4][2], const pg8::Unit& u, int wr, int wc, int fr, int fq) const {
;     ...
;             const int region = u.pn >> 2; const int c0 = (u.pn & 3) * 256 + cb;
; #pragma unroll
;             for (int ai = 0; ai < 2; ++ai)
; #pragma unroll
;                 for (int m = 0; m < 4; ++m) {
;                     const int row = lrow0 + ai * 128 + m * 16;
;                     const float rs = rsqrtf(ssq[row] * (1.f / 1024.f) + EPS);
;                     float s1 = 0.f, s2 = 0.f;
; #pragma unroll
;                     for (int bj = 0; bj < 2; ++bj) {
;                         const int c = c0 + bj * 128; const size_t off = (size_t)row * 1024 + c;
;                         const f32x4 v0 = acc[ai][bj][m][0] * rs, v1 = acc[ai][bj][m][1] * rs;
;                         const float v[8] = {v0[0], v0[1], v0[2], v0[3], v1[0], v1[1], v1[2], v1[3]};
;                         float y[8];
;                         if (region == 0) {
; #pragma unroll
;                             for (int j = 0; j < 8; ++j) y[j] = gelu_f(v[j]);
;                             *(v4u*)(o0 + off) = pack8(y);
;                         } else if (region == 1) {
; #pragma unroll
;                             for (int j = 0; j < 8; ++j) { y[j] = gelu_f(v[j]); s1 += y[j]; s2 += y[j] * y[j]; }
;                             *(v4u*)(o1 + off) = pack8(y);
;                         } else {
; #pragma unroll
;                             for (int j = 0; j < 8; ++j) y[j] = silu_f(v[j]);
;                             *(v4u*)(Y + off) = pack8(y);
.LBB0_547:
	v_lshl_add_u32 v166, s20, 8, v147
	v_readlane_b32 s20, v252, 60
	v_ashrrev_i32_e32 v167, 31, v166
	v_readlane_b32 s21, v252, 61
	s_cmp_gt_u32 s31, 3
	s_cselect_b64 s[2:3], -1, 0
	v_lshl_add_u64 v[168:169], v[166:167], 2, s[20:21]
	global_load_dword v196, v[168:169], off offset:64
	global_load_dword v197, v[168:169], off offset:128
	global_load_dword v198, v[168:169], off offset:192
	global_load_dword v199, v[168:169], off offset:512
	global_load_dword v200, v[168:169], off offset:576
	global_load_dword v201, v[168:169], off offset:640
	global_load_dword v202, v[168:169], off offset:704
	global_load_dword v1, v[168:169], off
	s_and_b32 s9, s31, -4
	s_cmp_eq_u32 s9, 4
	s_cselect_b64 s[0:1], -1, 0
	s_cmp_lg_u32 s9, 4
	s_cselect_b64 s[18:19], -1, 0
	s_mov_b64 s[20:21], -1
	s_waitcnt vmcnt(0)
	v_fmamk_f32 v1, v1, 0x3a800000, v139
	v_cmp_gt_f32_e32 vcc, s33, v1
	v_mul_f32_e32 v150, 0x4b800000, v1
	s_nop 0
	v_cndmask_b32_e32 v1, v1, v150, vcc
	v_rsq_f32_e32 v1, v1
	s_nop 0
	v_mul_f32_e32 v150, 0x45800000, v1
	v_cndmask_b32_e32 v170, v1, v150, vcc
	v_cndmask_b32_e64 v1, 0, 1, s[18:19]
	v_pk_mul_f32 v[128:129], v[128:129], v[170:171] op_sel_hi:[1,0]
	v_pk_mul_f32 v[172:173], v[126:127], v[170:171] op_sel_hi:[1,0]
	v_pk_mul_f32 v[126:127], v[124:125], v[170:171] op_sel_hi:[1,0]
	v_pk_mul_f32 v[122:123], v[122:123], v[170:171] op_sel_hi:[1,0]
	s_and_b64 vcc, exec, s[2:3]
	v_cmp_ne_u32_e64 s[46:47], 1, v1
	s_cbranch_vccz .LBB0_552
	s_and_b64 vcc, exec, s[46:47]
	s_mov_b64 s[18:19], -1
	s_cbranch_vccnz .LBB0_550
	v_mul_f32_e32 v1, 0xbfb8aa3b, v172
	v_exp_f32_e32 v1, v1
	v_mul_f32_e32 v124, 0xbfb8aa3b, v173
	v_exp_f32_e32 v124, v124
	v_mul_f32_e32 v150, 0xbfb8aa3b, v129
	v_add_f32_e32 v1, 1.0, v1
	v_exp_f32_e32 v151, v150
	v_add_f32_e32 v125, 1.0, v124
	v_rcp_f32_e32 v124, v1
	v_mul_f32_e32 v1, 0xbfb8aa3b, v128
	v_exp_f32_e32 v1, v1
	v_rcp_f32_e32 v125, v125
	s_mov_b64 s[18:19], 0
	v_add_f32_e32 v1, 1.0, v1
	v_rcp_f32_e32 v150, v1
	v_add_f32_e32 v1, 1.0, v151
	v_mul_f32_e32 v151, 0xbfb8aa3b, v122
	v_exp_f32_e32 v152, v151
	v_mul_f32_e32 v151, 0xbfb8aa3b, v123
	v_exp_f32_e32 v153, v151
	v_rcp_f32_e32 v151, v1
	v_add_f32_e32 v1, 1.0, v152
	v_rcp_f32_e32 v152, v1
	v_add_f32_e32 v1, 1.0, v153
	v_mul_f32_e32 v153, 0xbfb8aa3b, v126
	v_exp_f32_e32 v154, v153
	v_mul_f32_e32 v153, 0xbfb8aa3b, v127
	v_exp_f32_e32 v155, v153
	v_rcp_f32_e32 v153, v1
	v_add_f32_e32 v1, 1.0, v154
	v_rcp_f32_e32 v154, v1
	v_add_f32_e32 v1, 1.0, v155
	v_rcp_f32_e32 v155, v1
	v_pk_mul_f32 v[174:175], v[172:173], v[124:125]
	v_pk_mul_f32 v[176:177], v[128:129], v[150:151]
	v_pk_mul_f32 v[178:179], v[122:123], v[152:153]
	v_pk_mul_f32 v[180:181], v[126:127], v[154:155]

; __device__ __forceinline__ float silu_f(float x) { return x * __builtin_amdgcn_rcpf(1.f + __expf(-x)); }
; __device__ __forceinline__ float gelu_f(float x) { const float u2 = 1.5957691216057308f * (x + 0.044715f * x * x * x); return x * __builtin_amdgcn_rcpf(1.f + __expf(-u2)); }
; __device__ __forceinline__ v4u pack8(const float (&y)[8]) { return (v4u){pk2(y[0], y[1]), pk2(y[2], y[3]), pk2(y[4], y[5]), pk2(y[6], y[7])}; }
;     __device__ __forceinline__ void operator()(const f32x4 (&acc)[2][2][4][2], const pg8::Unit& u, int wr, int wc, int fr, int fq) const {
;     ...
;                 for (int m = 0; m < 4; ++m) {
;                     const int row = lrow0 + ai * 128 + m * 16;
;                     const float rs = rsqrtf(ssq[row] * (1.f / 1024.f) + EPS);
;                     float s1 = 0.f, s2 = 0.f;
; #pragma unroll
;                     for (int bj = 0; bj < 2; ++bj) {
;                         const int c = c0 + bj * 128; const size_t off = (size_t)row * 1024 + c;
;                         const f32x4 v0 = acc[ai][bj][m][0] * rs, v1 = acc[ai][bj][m][1] * rs;
;                         const float v[8] = {v0[0], v0[1], v0[2], v0[3], v1[0], v1[1], v1[2], v1[3]};
;                         float y[8];
;                         if (region == 0) {
; #pragma unroll
;                             for (int j = 0; j < 8; ++j) y[j] = gelu_f(v[j]);
;                             *(v4u*)(o0 + off) = pack8(y);
;                         } else if (region == 1) {
; #pragma unroll
;                             for (int j = 0; j < 8; ++j) { y[j] = gelu_f(v[j]); s1 += y[j]; s2 += y[j] * y[j]; }
;                             *(v4u*)(o1 + off) = pack8(y);
;                         } else {
; #pragma unroll
;                             for (int j = 0; j < 8; ++j) y[j] = silu_f(v[j]);
;                             *(v4u*)(Y + off) = pack8(y);
.LBB0_566:
	s_waitcnt lgkmcnt(1)
	v_or_b32_e32 v114, 16, v166
	v_readlane_b32 s0, v252, 60
	v_ashrrev_i32_e32 v115, 31, v114
	v_readlane_b32 s1, v252, 61
	s_and_b64 vcc, exec, s[48:49]
	s_mov_b64 s[2:3], -1
	s_waitcnt lgkmcnt(0)
	v_lshl_add_u64 v[116:117], v[114:115], 2, s[0:1]
	v_mov_b32_e32 v1, v196
	v_fmamk_f32 v1, v1, 0x3a800000, v139
	v_mul_f32_e32 v116, 0x4b800000, v1
	v_cmp_gt_f32_e64 s[0:1], s33, v1
	s_nop 1
	v_cndmask_b32_e64 v1, v1, v116, s[0:1]
	v_rsq_f32_e32 v1, v1
	s_nop 0
	v_mul_f32_e32 v116, 0x45800000, v1
	v_cndmask_b32_e64 v116, v1, v116, s[0:1]
	v_pk_mul_f32 v[112:113], v[112:113], v[116:117] op_sel_hi:[1,0]
	v_pk_mul_f32 v[120:121], v[110:111], v[116:117] op_sel_hi:[1,0]
	v_pk_mul_f32 v[108:109], v[108:109], v[116:117] op_sel_hi:[1,0]
	v_pk_mul_f32 v[110:111], v[106:107], v[116:117] op_sel_hi:[1,0]
	s_cbranch_vccnz .LBB0_571
	s_and_b64 vcc, exec, s[46:47]
	s_mov_b64 s[0:1], -1
	s_cbranch_vccnz .LBB0_569
	v_mul_f32_e32 v1, 0xbfb8aa3b, v120
	v_exp_f32_e32 v1, v1
	v_mul_f32_e32 v106, 0xbfb8aa3b, v121
	v_exp_f32_e32 v106, v106
	v_mul_f32_e32 v117, 0xbfb8aa3b, v113
	v_add_f32_e32 v1, 1.0, v1
	v_exp_f32_e32 v117, v117
	v_add_f32_e32 v107, 1.0, v106
	v_rcp_f32_e32 v106, v1
	v_mul_f32_e32 v1, 0xbfb8aa3b, v112
	v_exp_f32_e32 v1, v1
	v_mul_f32_e32 v118, 0xbfb8aa3b, v111
	v_exp_f32_e32 v118, v118
	v_rcp_f32_e32 v107, v107
	v_add_f32_e32 v1, 1.0, v1
	v_rcp_f32_e32 v124, v1
	v_add_f32_e32 v1, 1.0, v117
	v_mul_f32_e32 v117, 0xbfb8aa3b, v110
	v_exp_f32_e32 v117, v117
	v_rcp_f32_e32 v125, v1
	s_mov_b64 s[0:1], 0
	v_add_f32_e32 v1, 1.0, v117
	v_mul_f32_e32 v117, 0xbfb8aa3b, v108
	v_rcp_f32_e32 v126, v1
	v_add_f32_e32 v1, 1.0, v118
	v_exp_f32_e32 v117, v117
	v_mul_f32_e32 v118, 0xbfb8aa3b, v109
	v_exp_f32_e32 v118, v118
	v_rcp_f32_e32 v127, v1
	v_add_f32_e32 v1, 1.0, v117
	v_rcp_f32_e32 v128, v1
	v_add_f32_e32 v1, 1.0, v118
	v_rcp_f32_e32 v129, v1
	v_pk_mul_f32 v[118:119], v[120:121], v[106:107]
	v_pk_mul_f32 v[124:125], v[112:113], v[124:125]
	v_pk_mul_f32 v[126:127], v[110:111], v[126:127]
	v_pk_mul_f32 v[128:129], v[108:109], v[128:129]

; __device__ __forceinline__ float silu_f(float x) { return x * __builtin_amdgcn_rcpf(1.f + __expf(-x)); }
; __device__ __forceinline__ float gelu_f(float x) { const float u2 = 1.5957691216057308f * (x + 0.044715f * x * x * x); return x * __builtin_amdgcn_rcpf(1.f + __expf(-u2)); }
; __device__ __forceinline__ v4u pack8(const float (&y)[8]) { return (v4u){pk2(y[0], y[1]), pk2(y[2], y[3]), pk2(y[4], y[5]), pk2(y[6], y[7])}; }
;     __device__ __forceinline__ void operator()(const f32x4 (&acc)[2][2][4][2], const pg8::Unit& u, int wr, int wc, int fr, int fq) const {
;     ...
;                 for (int m = 0; m < 4; ++m) {
;                     const int row = lrow0 + ai * 128 + m * 16;
;                     const float rs = rsqrtf(ssq[row] * (1.f / 1024.f) + EPS);
;                     float s1 = 0.f, s2 = 0.f;
; #pragma unroll
;                     for (int bj = 0; bj < 2; ++bj) {
;                         const int c = c0 + bj * 128; const size_t off = (size_t)row * 1024 + c;
;                         const f32x4 v0 = acc[ai][bj][m][0] * rs, v1 = acc[ai][bj][m][1] * rs;
;                         const float v[8] = {v0[0], v0[1], v0[2], v0[3], v1[0], v1[1], v1[2], v1[3]};
;                         float y[8];
;                         if (region == 0) {
; #pragma unroll
;                             for (int j = 0; j < 8; ++j) y[j] = gelu_f(v[j]);
;                             *(v4u*)(o0 + off) = pack8(y);
;                         } else if (region == 1) {
; #pragma unroll
;                             for (int j = 0; j < 8; ++j) { y[j] = gelu_f(v[j]); s1 += y[j]; s2 += y[j] * y[j]; }
;                             *(v4u*)(o1 + off) = pack8(y);
;                         } else {
; #pragma unroll
;                             for (int j = 0; j < 8; ++j) y[j] = silu_f(v[j]);
;                             *(v4u*)(Y + off) = pack8(y);
.LBB0_585:
	s_waitcnt lgkmcnt(1)
	v_or_b32_e32 v98, 32, v166
	v_readlane_b32 s0, v252, 60
	v_ashrrev_i32_e32 v99, 31, v98
	v_readlane_b32 s1, v252, 61
	s_and_b64 vcc, exec, s[48:49]
	s_mov_b64 s[2:3], -1
	s_waitcnt lgkmcnt(0)
	v_lshl_add_u64 v[100:101], v[98:99], 2, s[0:1]
	v_mov_b32_e32 v1, v197
	v_fmamk_f32 v1, v1, 0x3a800000, v139
	v_mul_f32_e32 v100, 0x4b800000, v1
	v_cmp_gt_f32_e64 s[0:1], s33, v1
	s_nop 1
	v_cndmask_b32_e64 v1, v1, v100, s[0:1]
	v_rsq_f32_e32 v1, v1
	s_nop 0
	v_mul_f32_e32 v100, 0x45800000, v1
	v_cndmask_b32_e64 v100, v1, v100, s[0:1]
	v_pk_mul_f32 v[96:97], v[96:97], v[100:101] op_sel_hi:[1,0]
	v_pk_mul_f32 v[104:105], v[94:95], v[100:101] op_sel_hi:[1,0]
	v_pk_mul_f32 v[92:93], v[92:93], v[100:101] op_sel_hi:[1,0]
	v_pk_mul_f32 v[94:95], v[90:91], v[100:101] op_sel_hi:[1,0]
	s_cbranch_vccnz .LBB0_590
	s_and_b64 vcc, exec, s[46:47]
	s_mov_b64 s[0:1], -1
	s_cbranch_vccnz .LBB0_588
	v_mul_f32_e32 v1, 0xbfb8aa3b, v104
	v_exp_f32_e32 v1, v1
	v_mul_f32_e32 v90, 0xbfb8aa3b, v105
	v_exp_f32_e32 v90, v90
	v_mul_f32_e32 v101, 0xbfb8aa3b, v97
	v_add_f32_e32 v1, 1.0, v1
	v_exp_f32_e32 v101, v101
	v_add_f32_e32 v91, 1.0, v90
	v_rcp_f32_e32 v90, v1
	v_mul_f32_e32 v1, 0xbfb8aa3b, v96
	v_exp_f32_e32 v1, v1
	v_mul_f32_e32 v102, 0xbfb8aa3b, v95
	v_exp_f32_e32 v102, v102
	v_rcp_f32_e32 v91, v91
	v_add_f32_e32 v1, 1.0, v1
	v_rcp_f32_e32 v106, v1
	v_add_f32_e32 v1, 1.0, v101
	v_mul_f32_e32 v101, 0xbfb8aa3b, v94
	v_exp_f32_e32 v101, v101
	v_rcp_f32_e32 v107, v1
	s_mov_b64 s[0:1], 0
	v_add_f32_e32 v1, 1.0, v101
	v_mul_f32_e32 v101, 0xbfb8aa3b, v92
	v_rcp_f32_e32 v108, v1
	v_add_f32_e32 v1, 1.0, v102
	v_exp_f32_e32 v101, v101
	v_mul_f32_e32 v102, 0xbfb8aa3b, v93
	v_exp_f32_e32 v102, v102
	v_rcp_f32_e32 v109, v1
	v_add_f32_e32 v1, 1.0, v101
	v_rcp_f32_e32 v110, v1
	v_add_f32_e32 v1, 1.0, v102
	v_rcp_f32_e32 v111, v1
	v_pk_mul_f32 v[102:103], v[104:105], v[90:91]
	v_pk_mul_f32 v[106:107], v[96:97], v[106:107]
	v_pk_mul_f32 v[108:109], v[94:95], v[108:109]
	v_pk_mul_f32 v[110:111], v[92:93], v[110:111]

; __device__ __forceinline__ float silu_f(float x) { return x * __builtin_amdgcn_rcpf(1.f + __expf(-x)); }
; __device__ __forceinline__ float gelu_f(float x) { const float u2 = 1.5957691216057308f * (x + 0.044715f * x * x * x); return x * __builtin_amdgcn_rcpf(1.f + __expf(-u2)); }
; __device__ __forceinline__ v4u pack8(const float (&y)[8]) { return (v4u){pk2(y[0], y[1]), pk2(y[2], y[3]), pk2(y[4], y[5]), pk2(y[6], y[7])}; }
;     __device__ __forceinline__ void operator()(const f32x4 (&acc)[2][2][4][2], const pg8::Unit& u, int wr, int wc, int fr, int fq) const {
;     ...
;                 for (int m = 0; m < 4; ++m) {
;                     const int row = lrow0 + ai * 128 + m * 16;
;                     const float rs = rsqrtf(ssq[row] * (1.f / 1024.f) + EPS);
;                     float s1 = 0.f, s2 = 0.f;
; #pragma unroll
;                     for (int bj = 0; bj < 2; ++bj) {
;                         const int c = c0 + bj * 128; const size_t off = (size_t)row * 1024 + c;
;                         const f32x4 v0 = acc[ai][bj][m][0] * rs, v1 = acc[ai][bj][m][1] * rs;
;                         const float v[8] = {v0[0], v0[1], v0[2], v0[3], v1[0], v1[1], v1[2], v1[3]};
;                         float y[8];
;                         if (region == 0) {
; #pragma unroll
;                             for (int j = 0; j < 8; ++j) y[j] = gelu_f(v[j]);
;                             *(v4u*)(o0 + off) = pack8(y);
;                         } else if (region == 1) {
; #pragma unroll
;                             for (int j = 0; j < 8; ++j) { y[j] = gelu_f(v[j]); s1 += y[j]; s2 += y[j] * y[j]; }
;                             *(v4u*)(o1 + off) = pack8(y);
;                         } else {
; #pragma unroll
;                             for (int j = 0; j < 8; ++j) y[j] = silu_f(v[j]);
;                             *(v4u*)(Y + off) = pack8(y);
.LBB0_604:
	s_waitcnt lgkmcnt(1)
	v_or_b32_e32 v82, 48, v166
	v_readlane_b32 s0, v252, 60
	v_ashrrev_i32_e32 v83, 31, v82
	v_readlane_b32 s1, v252, 61
	s_and_b64 vcc, exec, s[48:49]
	s_mov_b64 s[2:3], -1
	s_waitcnt lgkmcnt(0)
	v_lshl_add_u64 v[84:85], v[82:83], 2, s[0:1]
	v_mov_b32_e32 v1, v198
	v_fmamk_f32 v1, v1, 0x3a800000, v139
	v_mul_f32_e32 v84, 0x4b800000, v1
	v_cmp_gt_f32_e64 s[0:1], s33, v1
	s_nop 1
	v_cndmask_b32_e64 v1, v1, v84, s[0:1]
	v_rsq_f32_e32 v1, v1
	s_nop 0
	v_mul_f32_e32 v84, 0x45800000, v1
	v_cndmask_b32_e64 v84, v1, v84, s[0:1]
	v_pk_mul_f32 v[80:81], v[80:81], v[84:85] op_sel_hi:[1,0]
	v_pk_mul_f32 v[88:89], v[78:79], v[84:85] op_sel_hi:[1,0]
	v_pk_mul_f32 v[76:77], v[76:77], v[84:85] op_sel_hi:[1,0]
	v_pk_mul_f32 v[78:79], v[74:75], v[84:85] op_sel_hi:[1,0]
	s_cbranch_vccnz .LBB0_609
	s_and_b64 vcc, exec, s[46:47]
	s_mov_b64 s[0:1], -1
	s_cbranch_vccnz .LBB0_607
	v_mul_f32_e32 v1, 0xbfb8aa3b, v88
	v_exp_f32_e32 v1, v1
	v_mul_f32_e32 v74, 0xbfb8aa3b, v89
	v_exp_f32_e32 v74, v74
	v_mul_f32_e32 v85, 0xbfb8aa3b, v81
	v_add_f32_e32 v1, 1.0, v1
	v_exp_f32_e32 v85, v85
	v_add_f32_e32 v75, 1.0, v74
	v_rcp_f32_e32 v74, v1
	v_mul_f32_e32 v1, 0xbfb8aa3b, v80
	v_exp_f32_e32 v1, v1
	v_mul_f32_e32 v86, 0xbfb8aa3b, v79
	v_exp_f32_e32 v86, v86
	v_rcp_f32_e32 v75, v75
	v_add_f32_e32 v1, 1.0, v1
	v_rcp_f32_e32 v90, v1
	v_add_f32_e32 v1, 1.0, v85
	v_mul_f32_e32 v85, 0xbfb8aa3b, v78
	v_exp_f32_e32 v85, v85
	v_rcp_f32_e32 v91, v1
	s_mov_b64 s[0:1], 0
	v_add_f32_e32 v1, 1.0, v85
	v_mul_f32_e32 v85, 0xbfb8aa3b, v76
	v_rcp_f32_e32 v92, v1
	v_add_f32_e32 v1, 1.0, v86
	v_exp_f32_e32 v85, v85
	v_mul_f32_e32 v86, 0xbfb8aa3b, v77
	v_exp_f32_e32 v86, v86
	v_rcp_f32_e32 v93, v1
	v_add_f32_e32 v1, 1.0, v85
	v_rcp_f32_e32 v94, v1
	v_add_f32_e32 v1, 1.0, v86
	v_rcp_f32_e32 v95, v1
	v_pk_mul_f32 v[86:87], v[88:89], v[74:75]
	v_pk_mul_f32 v[90:91], v[80:81], v[90:91]
	v_pk_mul_f32 v[92:93], v[78:79], v[92:93]
	v_pk_mul_f32 v[94:95], v[76:77], v[94:95]

; __device__ __forceinline__ float silu_f(float x) { return x * __builtin_amdgcn_rcpf(1.f + __expf(-x)); }
; __device__ __forceinline__ float gelu_f(float x) { const float u2 = 1.5957691216057308f * (x + 0.044715f * x * x * x); return x * __builtin_amdgcn_rcpf(1.f + __expf(-u2)); }
; __device__ __forceinline__ v4u pack8(const float (&y)[8]) { return (v4u){pk2(y[0], y[1]), pk2(y[2], y[3]), pk2(y[4], y[5]), pk2(y[6], y[7])}; }
;     __device__ __forceinline__ void operator()(const f32x4 (&acc)[2][2][4][2], const pg8::Unit& u, int wr, int wc, int fr, int fq) const {
;     ...
;                 for (int m = 0; m < 4; ++m) {
;                     const int row = lrow0 + ai * 128 + m * 16;
;                     const float rs = rsqrtf(ssq[row] * (1.f / 1024.f) + EPS);
;                     float s1 = 0.f, s2 = 0.f;
; #pragma unroll
;                     for (int bj = 0; bj < 2; ++bj) {
;                         const int c = c0 + bj * 128; const size_t off = (size_t)row * 1024 + c;
;                         const f32x4 v0 = acc[ai][bj][m][0] * rs, v1 = acc[ai][bj][m][1] * rs;
;                         const float v[8] = {v0[0], v0[1], v0[2], v0[3], v1[0], v1[1], v1[2], v1[3]};
;                         float y[8];
;                         if (region == 0) {
; #pragma unroll
;                             for (int j = 0; j < 8; ++j) y[j] = gelu_f(v[j]);
;                             *(v4u*)(o0 + off) = pack8(y);
;                         } else if (region == 1) {
; #pragma unroll
;                             for (int j = 0; j < 8; ++j) { y[j] = gelu_f(v[j]); s1 += y[j]; s2 += y[j] * y[j]; }
;                             *(v4u*)(o1 + off) = pack8(y);
;                         } else {
; #pragma unroll
;                             for (int j = 0; j < 8; ++j) y[j] = silu_f(v[j]);
;                             *(v4u*)(Y + off) = pack8(y);
.LBB0_623:
	v_mov_b32_e32 v1, v199
	s_and_b64 vcc, exec, s[48:49]
	s_mov_b64 s[2:3], -1
	v_fmamk_f32 v1, v1, 0x3a800000, v139
	s_waitcnt lgkmcnt(1)
	v_mul_f32_e32 v66, 0x4b800000, v1
	v_cmp_gt_f32_e64 s[0:1], s33, v1
	s_nop 1
	v_cndmask_b32_e64 v1, v1, v66, s[0:1]
	v_rsq_f32_e32 v1, v1
	s_nop 0
	v_mul_f32_e32 v66, 0x45800000, v1
	v_cndmask_b32_e64 v66, v1, v66, s[0:1]
	v_pk_mul_f32 v[64:65], v[64:65], v[66:67] op_sel_hi:[1,0]
	v_pk_mul_f32 v[70:71], v[62:63], v[66:67] op_sel_hi:[1,0]
	v_pk_mul_f32 v[62:63], v[60:61], v[66:67] op_sel_hi:[1,0]
	v_pk_mul_f32 v[58:59], v[58:59], v[66:67] op_sel_hi:[1,0]
	s_cbranch_vccnz .LBB0_628
	s_and_b64 vcc, exec, s[46:47]
	s_mov_b64 s[0:1], -1
	s_cbranch_vccnz .LBB0_626
	v_mul_f32_e32 v1, 0xbfb8aa3b, v70
	v_exp_f32_e32 v1, v1
	v_mul_f32_e32 v60, 0xbfb8aa3b, v71
	v_exp_f32_e32 v60, v60
	v_mul_f32_e32 v67, 0xbfb8aa3b, v65
	v_add_f32_e32 v1, 1.0, v1
	v_exp_f32_e32 v67, v67
	v_add_f32_e32 v61, 1.0, v60
	v_rcp_f32_e32 v60, v1
	v_mul_f32_e32 v1, 0xbfb8aa3b, v64
	v_exp_f32_e32 v1, v1
	s_waitcnt lgkmcnt(0)
	v_mul_f32_e32 v68, 0xbfb8aa3b, v59
	v_exp_f32_e32 v68, v68
	v_rcp_f32_e32 v61, v61
	v_add_f32_e32 v1, 1.0, v1
	v_rcp_f32_e32 v72, v1
	v_add_f32_e32 v1, 1.0, v67
	v_mul_f32_e32 v67, 0xbfb8aa3b, v58
	v_exp_f32_e32 v67, v67
	v_rcp_f32_e32 v73, v1
	s_mov_b64 s[0:1], 0
	v_add_f32_e32 v1, 1.0, v67
	v_mul_f32_e32 v67, 0xbfb8aa3b, v62
	v_rcp_f32_e32 v74, v1
	v_add_f32_e32 v1, 1.0, v68
	v_exp_f32_e32 v67, v67
	v_mul_f32_e32 v68, 0xbfb8aa3b, v63
	v_exp_f32_e32 v68, v68
	v_rcp_f32_e32 v75, v1
	v_add_f32_e32 v1, 1.0, v67
	v_rcp_f32_e32 v76, v1
	v_add_f32_e32 v1, 1.0, v68
	v_rcp_f32_e32 v77, v1
	v_pk_mul_f32 v[68:69], v[70:71], v[60:61]
	v_pk_mul_f32 v[72:73], v[64:65], v[72:73]
	v_pk_mul_f32 v[74:75], v[58:59], v[74:75]
	v_pk_mul_f32 v[76:77], v[62:63], v[76:77]

; __device__ __forceinline__ float silu_f(float x) { return x * __builtin_amdgcn_rcpf(1.f + __expf(-x)); }
; __device__ __forceinline__ float gelu_f(float x) { const float u2 = 1.5957691216057308f * (x + 0.044715f * x * x * x); return x * __builtin_amdgcn_rcpf(1.f + __expf(-u2)); }
; __device__ __forceinline__ v4u pack8(const float (&y)[8]) { return (v4u){pk2(y[0], y[1]), pk2(y[2], y[3]), pk2(y[4], y[5]), pk2(y[6], y[7])}; }
;     __device__ __forceinline__ void operator()(const f32x4 (&acc)[2][2][4][2], const pg8::Unit& u, int wr, int wc, int fr, int fq) const {
;     ...
;                 for (int m = 0; m < 4; ++m) {
;                     const int row = lrow0 + ai * 128 + m * 16;
;                     const float rs = rsqrtf(ssq[row] * (1.f / 1024.f) + EPS);
;                     float s1 = 0.f, s2 = 0.f;
; #pragma unroll
;                     for (int bj = 0; bj < 2; ++bj) {
;                         const int c = c0 + bj * 128; const size_t off = (size_t)row * 1024 + c;
;                         const f32x4 v0 = acc[ai][bj][m][0] * rs, v1 = acc[ai][bj][m][1] * rs;
;                         const float v[8] = {v0[0], v0[1], v0[2], v0[3], v1[0], v1[1], v1[2], v1[3]};
;                         float y[8];
;                         if (region == 0) {
; #pragma unroll
;                             for (int j = 0; j < 8; ++j) y[j] = gelu_f(v[j]);
;                             *(v4u*)(o0 + off) = pack8(y);
;                         } else if (region == 1) {
; #pragma unroll
;                             for (int j = 0; j < 8; ++j) { y[j] = gelu_f(v[j]); s1 += y[j]; s2 += y[j] * y[j]; }
;                             *(v4u*)(o1 + off) = pack8(y);
;                         } else {
; #pragma unroll
;                             for (int j = 0; j < 8; ++j) y[j] = silu_f(v[j]);
;                             *(v4u*)(Y + off) = pack8(y);
.LBB0_642:
	v_mov_b32_e32 v1, v200
	s_and_b64 vcc, exec, s[48:49]
	s_mov_b64 s[2:3], -1
	v_fmamk_f32 v1, v1, 0x3a800000, v139
	s_waitcnt lgkmcnt(1)
	v_mul_f32_e32 v50, 0x4b800000, v1
	v_cmp_gt_f32_e64 s[0:1], s33, v1
	s_nop 1
	v_cndmask_b32_e64 v1, v1, v50, s[0:1]
	v_rsq_f32_e32 v1, v1
	s_nop 0
	v_mul_f32_e32 v50, 0x45800000, v1
	v_cndmask_b32_e64 v50, v1, v50, s[0:1]
	v_pk_mul_f32 v[48:49], v[48:49], v[50:51] op_sel_hi:[1,0]
	v_pk_mul_f32 v[54:55], v[46:47], v[50:51] op_sel_hi:[1,0]
	v_pk_mul_f32 v[46:47], v[44:45], v[50:51] op_sel_hi:[1,0]
	v_pk_mul_f32 v[42:43], v[42:43], v[50:51] op_sel_hi:[1,0]
	s_cbranch_vccnz .LBB0_647
	s_and_b64 vcc, exec, s[46:47]
	s_mov_b64 s[0:1], -1
	s_cbranch_vccnz .LBB0_645
	v_mul_f32_e32 v1, 0xbfb8aa3b, v54
	v_exp_f32_e32 v1, v1
	v_mul_f32_e32 v44, 0xbfb8aa3b, v55
	v_exp_f32_e32 v44, v44
	v_mul_f32_e32 v51, 0xbfb8aa3b, v49
	v_add_f32_e32 v1, 1.0, v1
	v_exp_f32_e32 v51, v51
	v_add_f32_e32 v45, 1.0, v44
	v_rcp_f32_e32 v44, v1
	v_mul_f32_e32 v1, 0xbfb8aa3b, v48
	v_exp_f32_e32 v1, v1
	s_waitcnt lgkmcnt(0)
	v_mul_f32_e32 v52, 0xbfb8aa3b, v43
	v_exp_f32_e32 v52, v52
	v_rcp_f32_e32 v45, v45
	v_add_f32_e32 v1, 1.0, v1
	v_rcp_f32_e32 v56, v1
	v_add_f32_e32 v1, 1.0, v51
	v_mul_f32_e32 v51, 0xbfb8aa3b, v42
	v_exp_f32_e32 v51, v51
	v_rcp_f32_e32 v57, v1
	s_mov_b64 s[0:1], 0
	v_add_f32_e32 v1, 1.0, v51
	v_mul_f32_e32 v51, 0xbfb8aa3b, v46
	v_rcp_f32_e32 v58, v1
	v_add_f32_e32 v1, 1.0, v52
	v_exp_f32_e32 v51, v51
	v_mul_f32_e32 v52, 0xbfb8aa3b, v47
	v_exp_f32_e32 v52, v52
	v_rcp_f32_e32 v59, v1
	v_add_f32_e32 v1, 1.0, v51
	v_rcp_f32_e32 v60, v1
	v_add_f32_e32 v1, 1.0, v52
	v_rcp_f32_e32 v61, v1
	v_pk_mul_f32 v[52:53], v[54:55], v[44:45]
	v_pk_mul_f32 v[56:57], v[48:49], v[56:57]
	v_pk_mul_f32 v[58:59], v[42:43], v[58:59]
	v_pk_mul_f32 v[60:61], v[46:47], v[60:61]

; __device__ __forceinline__ float silu_f(float x) { return x * __builtin_amdgcn_rcpf(1.f + __expf(-x)); }
; __device__ __forceinline__ float gelu_f(float x) { const float u2 = 1.5957691216057308f * (x + 0.044715f * x * x * x); return x * __builtin_amdgcn_rcpf(1.f + __expf(-u2)); }
; __device__ __forceinline__ v4u pack8(const float (&y)[8]) { return (v4u){pk2(y[0], y[1]), pk2(y[2], y[3]), pk2(y[4], y[5]), pk2(y[6], y[7])}; }
;     __device__ __forceinline__ void operator()(const f32x4 (&acc)[2][2][4][2], const pg8::Unit& u, int wr, int wc, int fr, int fq) const {
;     ...
;                 for (int m = 0; m < 4; ++m) {
;                     const int row = lrow0 + ai * 128 + m * 16;
;                     const float rs = rsqrtf(ssq[row] * (1.f / 1024.f) + EPS);
;                     float s1 = 0.f, s2 = 0.f;
; #pragma unroll
;                     for (int bj = 0; bj < 2; ++bj) {
;                         const int c = c0 + bj * 128; const size_t off = (size_t)row * 1024 + c;
;                         const f32x4 v0 = acc[ai][bj][m][0] * rs, v1 = acc[ai][bj][m][1] * rs;
;                         const float v[8] = {v0[0], v0[1], v0[2], v0[3], v1[0], v1[1], v1[2], v1[3]};
;                         float y[8];
;                         if (region == 0) {
; #pragma unroll
;                             for (int j = 0; j < 8; ++j) y[j] = gelu_f(v[j]);
;                             *(v4u*)(o0 + off) = pack8(y);
;                         } else if (region == 1) {
; #pragma unroll
;                             for (int j = 0; j < 8; ++j) { y[j] = gelu_f(v[j]); s1 += y[j]; s2 += y[j] * y[j]; }
;                             *(v4u*)(o1 + off) = pack8(y);
;                         } else {
; #pragma unroll
;                             for (int j = 0; j < 8; ++j) y[j] = silu_f(v[j]);
;                             *(v4u*)(Y + off) = pack8(y);
.LBB0_661:
	v_mov_b32_e32 v1, v201
	s_and_b64 vcc, exec, s[48:49]
	s_mov_b64 s[2:3], -1
	v_fmamk_f32 v1, v1, 0x3a800000, v139
	s_waitcnt lgkmcnt(1)
	v_mul_f32_e32 v34, 0x4b800000, v1
	v_cmp_gt_f32_e64 s[0:1], s33, v1
	s_nop 1
	v_cndmask_b32_e64 v1, v1, v34, s[0:1]
	v_rsq_f32_e32 v1, v1
	s_nop 0
	v_mul_f32_e32 v34, 0x45800000, v1
	v_cndmask_b32_e64 v34, v1, v34, s[0:1]
	v_pk_mul_f32 v[32:33], v[32:33], v[34:35] op_sel_hi:[1,0]
	v_pk_mul_f32 v[38:39], v[30:31], v[34:35] op_sel_hi:[1,0]
	v_pk_mul_f32 v[30:31], v[28:29], v[34:35] op_sel_hi:[1,0]
	v_pk_mul_f32 v[26:27], v[26:27], v[34:35] op_sel_hi:[1,0]
	s_cbranch_vccnz .LBB0_666
	s_and_b64 vcc, exec, s[46:47]
	s_mov_b64 s[0:1], -1
	s_cbranch_vccnz .LBB0_664
	v_mul_f32_e32 v1, 0xbfb8aa3b, v38
	v_exp_f32_e32 v1, v1
	v_mul_f32_e32 v28, 0xbfb8aa3b, v39
	v_exp_f32_e32 v28, v28
	v_mul_f32_e32 v35, 0xbfb8aa3b, v33
	v_add_f32_e32 v1, 1.0, v1
	v_exp_f32_e32 v35, v35
	v_add_f32_e32 v29, 1.0, v28
	v_rcp_f32_e32 v28, v1
	v_mul_f32_e32 v1, 0xbfb8aa3b, v32
	v_exp_f32_e32 v1, v1
	s_waitcnt lgkmcnt(0)
	v_mul_f32_e32 v36, 0xbfb8aa3b, v27
	v_exp_f32_e32 v36, v36
	v_rcp_f32_e32 v29, v29
	v_add_f32_e32 v1, 1.0, v1
	v_rcp_f32_e32 v40, v1
	v_add_f32_e32 v1, 1.0, v35
	v_mul_f32_e32 v35, 0xbfb8aa3b, v26
	v_exp_f32_e32 v35, v35
	v_rcp_f32_e32 v41, v1
	s_mov_b64 s[0:1], 0
	v_add_f32_e32 v1, 1.0, v35
	v_mul_f32_e32 v35, 0xbfb8aa3b, v30
	v_rcp_f32_e32 v42, v1
	v_add_f32_e32 v1, 1.0, v36
	v_exp_f32_e32 v35, v35
	v_mul_f32_e32 v36, 0xbfb8aa3b, v31
	v_exp_f32_e32 v36, v36
	v_rcp_f32_e32 v43, v1
	v_add_f32_e32 v1, 1.0, v35
	v_rcp_f32_e32 v44, v1
	v_add_f32_e32 v1, 1.0, v36
	v_rcp_f32_e32 v45, v1
	v_pk_mul_f32 v[36:37], v[38:39], v[28:29]
	v_pk_mul_f32 v[40:41], v[32:33], v[40:41]
	v_pk_mul_f32 v[42:43], v[26:27], v[42:43]
	v_pk_mul_f32 v[44:45], v[30:31], v[44:45]

; __device__ __forceinline__ float silu_f(float x) { return x * __builtin_amdgcn_rcpf(1.f + __expf(-x)); }
; __device__ __forceinline__ float gelu_f(float x) { const float u2 = 1.5957691216057308f * (x + 0.044715f * x * x * x); return x * __builtin_amdgcn_rcpf(1.f + __expf(-u2)); }
; __device__ __forceinline__ v4u pack8(const float (&y)[8]) { return (v4u){pk2(y[0], y[1]), pk2(y[2], y[3]), pk2(y[4], y[5]), pk2(y[6], y[7])}; }
;     __device__ __forceinline__ void operator()(const f32x4 (&acc)[2][2][4][2], const pg8::Unit& u, int wr, int wc, int fr, int fq) const {
;     ...
;                 for (int m = 0; m < 4; ++m) {
;                     const int row = lrow0 + ai * 128 + m * 16;
;                     const float rs = rsqrtf(ssq[row] * (1.f / 1024.f) + EPS);
;                     float s1 = 0.f, s2 = 0.f;
; #pragma unroll
;                     for (int bj = 0; bj < 2; ++bj) {
;                         const int c = c0 + bj * 128; const size_t off = (size_t)row * 1024 + c;
;                         const f32x4 v0 = acc[ai][bj][m][0] * rs, v1 = acc[ai][bj][m][1] * rs;
;                         const float v[8] = {v0[0], v0[1], v0[2], v0[3], v1[0], v1[1], v1[2], v1[3]};
;                         float y[8];
;                         if (region == 0) {
; #pragma unroll
;                             for (int j = 0; j < 8; ++j) y[j] = gelu_f(v[j]);
;                             *(v4u*)(o0 + off) = pack8(y);
;                         } else if (region == 1) {
; #pragma unroll
;                             for (int j = 0; j < 8; ++j) { y[j] = gelu_f(v[j]); s1 += y[j]; s2 += y[j] * y[j]; }
;                             *(v4u*)(o1 + off) = pack8(y);
;                         } else {
; #pragma unroll
;                             for (int j = 0; j < 8; ++j) y[j] = silu_f(v[j]);
;                             *(v4u*)(Y + off) = pack8(y);
.LBB0_680:
	v_mov_b32_e32 v1, v202
	s_and_b64 vcc, exec, s[48:49]
	s_mov_b64 s[2:3], -1
	v_fmamk_f32 v1, v1, 0x3a800000, v139
	s_waitcnt lgkmcnt(1)
	v_mul_f32_e32 v18, 0x4b800000, v1
	v_cmp_gt_f32_e64 s[0:1], s33, v1
	s_nop 1
	v_cndmask_b32_e64 v1, v1, v18, s[0:1]
	v_rsq_f32_e32 v1, v1
	s_nop 0
	v_mul_f32_e32 v18, 0x45800000, v1
	v_cndmask_b32_e64 v18, v1, v18, s[0:1]
	v_pk_mul_f32 v[16:17], v[16:17], v[18:19] op_sel_hi:[1,0]
	v_pk_mul_f32 v[22:23], v[14:15], v[18:19] op_sel_hi:[1,0]
	v_pk_mul_f32 v[14:15], v[12:13], v[18:19] op_sel_hi:[1,0]
	v_pk_mul_f32 v[10:11], v[10:11], v[18:19] op_sel_hi:[1,0]
	s_cbranch_vccnz .LBB0_685
	s_and_b64 vcc, exec, s[46:47]
	s_mov_b64 s[0:1], -1
	s_cbranch_vccnz .LBB0_683
	v_mul_f32_e32 v1, 0xbfb8aa3b, v22
	v_exp_f32_e32 v1, v1
	v_mul_f32_e32 v12, 0xbfb8aa3b, v23
	v_exp_f32_e32 v12, v12
	v_mul_f32_e32 v19, 0xbfb8aa3b, v17
	v_add_f32_e32 v1, 1.0, v1
	v_exp_f32_e32 v19, v19
	v_add_f32_e32 v13, 1.0, v12
	v_rcp_f32_e32 v12, v1
	v_mul_f32_e32 v1, 0xbfb8aa3b, v16
	v_exp_f32_e32 v1, v1
	s_waitcnt lgkmcnt(0)
	v_mul_f32_e32 v20, 0xbfb8aa3b, v11
	v_exp_f32_e32 v20, v20
	v_rcp_f32_e32 v13, v13
	v_add_f32_e32 v1, 1.0, v1
	v_rcp_f32_e32 v24, v1
	v_add_f32_e32 v1, 1.0, v19
	v_mul_f32_e32 v19, 0xbfb8aa3b, v10
	v_exp_f32_e32 v19, v19
	v_rcp_f32_e32 v25, v1
	s_mov_b64 s[0:1], 0
	v_add_f32_e32 v1, 1.0, v19
	v_mul_f32_e32 v19, 0xbfb8aa3b, v14
	v_rcp_f32_e32 v26, v1
	v_add_f32_e32 v1, 1.0, v20
	v_exp_f32_e32 v19, v19
	v_mul_f32_e32 v20, 0xbfb8aa3b, v15
	v_exp_f32_e32 v20, v20
	v_rcp_f32_e32 v27, v1
	v_add_f32_e32 v1, 1.0, v19
	v_rcp_f32_e32 v28, v1
	v_add_f32_e32 v1, 1.0, v20
	v_rcp_f32_e32 v29, v1
	v_pk_mul_f32 v[20:21], v[22:23], v[12:13]
	v_pk_mul_f32 v[24:25], v[16:17], v[24:25]
	v_pk_mul_f32 v[26:27], v[10:11], v[26:27]
	v_pk_mul_f32 v[28:29], v[14:15], v[28:29]
